# attention loop: K/bias fragments prefetched after the barrier under the PV MFMAs, PV(u0) interleaved with exp(u1), P fragments converted in place
# speedup vs baseline: 1.1097x; 1.0007x over previous
; __device__ __forceinline__ void attn_block(const Params& P, int bh, int qb, unsigned char* smem) {
;     ...
;     auto load_tile = [&](int kv) {
;         const int key0 = kv * 64 + srow0, key1 = key0 + 32;
;         const bf16_t* p0 = z + (size_t)(b * L + (key0 < L ? key0 : L - 1)) * NZ + h * 64 + sch * 8;
;         const bf16_t* p1 = z + (size_t)(b * L + (key1 < L ? key1 : L - 1)) * NZ + h * 64 + sch * 8;
;         rk0 = *(const uint4*)(p0 + ZC_FK); rv0 = *(const uint4*)(p0 + ZC_FV);
;         rk1 = *(const uint4*)(p1 + ZC_FK); rv1 = *(const uint4*)(p1 + ZC_FV);
;         const int keyc = kv * 64 + (tid & 63);
;         rc = cum[keyc < L ? keyc : L - 1];
;     };
;     auto store_tile = [&](int buf) {
;         unsigned char* sK = smem + buf * 16384; unsigned char* sV = sK + 8192;
;         const int row0 = srow0, row1 = srow0 + 32;
;         *(uint4*)(sK + row0 * 128 + ((sch ^ (row0 & 7)) << 4)) = rk0;
;         *(uint4*)(sV + vimg_off(row0, sch)) = rv0;
;         *(uint4*)(sK + row1 * 128 + ((sch ^ (row1 & 7)) << 4)) = rk1;
;         *(uint4*)(sV + vimg_off(row1, sch)) = rv1;
;         if (tid < 64) ((float*)(smem + 32768 + buf * 256))[tid] = rc;
;     };
;     float m[2] = {-1e30f, -1e30f};
;     f32x4 o[2][5];
; #pragma unroll
;     for (int u = 0; u < 2; ++u)
; #pragma unroll
;         for (int c = 0; c < 5; ++c) o[u][c] = (f32x4){0.f, 0.f, 0.f, 0.f};
;     const unsigned onew = (lr == 0) ? 0x3F803F80u : 0u;
;     const bf16x8 vones = __builtin_bit_cast(bf16x8, make_uint4(onew, onew, onew, onew));
;     load_tile(nkv - 1); store_tile((nkv - 1) & 1);
;     __syncthreads();
;     if (nkv > 1) load_tile(nkv - 2);
;     ...
;         const int buf = kv & 1;
;         const unsigned char* sK = smem + buf * 16384; const unsigned char* sV = sK + 8192;
;         const float* sck = (const float*)(smem + 32768 + buf * 256);
;         f32x4 sa[2][4];
; #pragma unroll
;         for (int c = 0; c < 4; ++c) {
;             sa[0][c] = (f32x4){0.f, 0.f, 0.f, 0.f}; sa[1][c] = (f32x4){0.f, 0.f, 0.f, 0.f};
; #pragma unroll
;             for (int s = 0; s < 2; ++s) {
;                 const bf16x8 kf = *(const bf16x8*)(sK + (16 * c + lr) * 128 + (((4 * s + g) ^ (lr & 7)) << 4));
;                 sa[0][c] = __builtin_amdgcn_mfma_f32_16x16x32_bf16(kf, qf[0][s], sa[0][c], 0, 0, 0);
;                 sa[1][c] = __builtin_amdgcn_mfma_f32_16x16x32_bf16(kf, qf[1][s], sa[1][c], 0, 0, 0);
.LBB0_707:
	s_or_b64 exec, exec, s[0:1]
	s_lshl_b32 s43, s43, 6
	s_add_i32 s68, s43, 0xffffff80
	v_add_u32_e32 v25, s68, v22
	v_min_i32_e32 v26, 0x80f, v25
	v_add_u32_e32 v28, s14, v26
	v_mov_b64_e32 v[26:27], s[80:81]
	v_lshlrev_b32_e32 v2, 3, v23
	v_mad_i64_i32 v[28:29], s[0:1], v28, s20, v[26:27]
	v_min_i32_e32 v25, 0x7ef, v25
	v_lshl_add_u64 v[28:29], v[28:29], 0, s[34:35]
	v_lshlrev_b32_e32 v2, 1, v2
	v_add_u32_e32 v25, s42, v25
	v_lshl_add_u64 v[28:29], v[28:29], 0, v[2:3]
	v_mad_i64_i32 v[26:27], s[0:1], v25, s20, v[26:27]
	v_lshl_add_u64 v[26:27], v[26:27], 0, s[34:35]
	v_add_co_u32_e32 v28, vcc, s87, v28
	v_lshl_add_u64 v[26:27], v[26:27], 0, v[2:3]
	s_nop 0
	v_addc_co_u32_e32 v29, vcc, 0, v29, vcc
	v_or_b32_e32 v25, s68, v24
	v_add_co_u32_e32 v26, vcc, s87, v26
	v_min_u32_e32 v25, 0x80f, v25
	s_nop 0
	v_addc_co_u32_e32 v27, vcc, 0, v27, vcc
	v_lshlrev_b32_e32 v25, 2, v25
	s_waitcnt lgkmcnt(0)
	s_barrier
	global_load_dwordx4 v[58:61], v[28:29], off offset:1024
	global_load_dwordx4 v[62:65], v[28:29], off offset:2048
	global_load_dwordx4 v[70:73], v[26:27], off offset:1024
	global_load_dwordx4 v[74:77], v[26:27], off offset:2048
	global_load_dword v179, v25, s[12:13]
	s_add_u32 s0, s80, s34
	s_addc_u32 s1, s81, 0
	v_lshl_add_u64 v[136:137], s[0:1], 0, v[2:3]
	v_lshlrev_b32_e32 v174, 2, v4
	v_lshrrev_b32_e32 v2, 2, v169
	v_or_b32_e32 v25, v174, v2
	v_bfe_u32 v27, v169, 1, 1
	v_bitop3_b32 v2, v174, 6, v2 bitop3:0xc8
	v_or_b32_e32 v2, v2, v27
	v_lshlrev_b32_e32 v177, 4, v2
	v_lshlrev_b32_e32 v2, 3, v169
	v_and_b32_e32 v138, 8, v2
	v_or_b32_e32 v2, 2, v27
	v_bitop3_b32 v2, v25, v2, 6 bitop3:0x6c
	v_lshlrev_b32_e32 v178, 4, v2
	v_or_b32_e32 v2, 4, v27
	v_lshrrev_b32_e32 v26, 1, v169
	v_bitop3_b32 v2, v25, v2, 6 bitop3:0x6c
	v_lshlrev_b32_e32 v180, 4, v2
	v_bitop3_b32 v2, v25, v26, 6 bitop3:0x4e
	v_lshlrev_b32_e32 v181, 4, v2
	v_xor_b32_e32 v2, v4, v23
	v_cmp_eq_u32_e32 vcc, 0, v169
	v_lshl_add_u32 v175, v4, 4, 0
	v_lshl_add_u32 v182, v5, 2, 0
	v_lshlrev_b32_e32 v183, 4, v2
	v_bitop3_b32 v2, v4, v23, 4 bitop3:0x36
	v_mov_b32_e32 v4, v3
	v_mov_b32_e32 v5, v3
	v_cndmask_b32_e32 v54, 0, v159, vcc
	v_lshlrev_b32_e32 v176, 7, v25
	v_lshlrev_b32_e32 v184, 4, v2
	v_or_b32_e32 v185, 0xffffff40, v24
	v_add_u32_e32 v186, 0xffffff40, v22
	v_mov_b32_e32 v2, v3
	v_mov_b64_e32 v[68:69], v[4:5]
	v_mov_b64_e32 v[52:53], v[4:5]
	v_mov_b64_e32 v[48:49], v[4:5]
	v_mov_b64_e32 v[44:45], v[4:5]
	v_mov_b64_e32 v[80:81], v[4:5]
	v_mov_b64_e32 v[36:37], v[4:5]
	v_mov_b64_e32 v[32:33], v[4:5]
	v_mov_b64_e32 v[28:29], v[4:5]
	v_mov_b64_e32 v[24:25], v[4:5]
	v_mov_b64_e32 v[40:41], v[4:5]
	v_mov_b32_e32 v55, v54
	v_mov_b32_e32 v56, v54
	v_mov_b32_e32 v57, v54
	v_lshlrev_b32_e32 v173, 7, v169
	v_mov_b32_e32 v187, 0xf149f2ca
	v_mov_b64_e32 v[66:67], v[2:3]
	v_mov_b64_e32 v[50:51], v[2:3]
	v_mov_b64_e32 v[46:47], v[2:3]
	v_mov_b64_e32 v[42:43], v[2:3]
	v_mov_b64_e32 v[78:79], v[2:3]
	v_mov_b64_e32 v[34:35], v[2:3]
	v_mov_b64_e32 v[30:31], v[2:3]
	v_mov_b64_e32 v[26:27], v[2:3]
	v_mov_b64_e32 v[22:23], v[2:3]
	v_mov_b64_e32 v[38:39], v[2:3]
	v_mov_b32_e32 v2, 0xf149f2ca
	v_mov_b32_e32 v196, 0x7149f2ca
	v_mov_b32_e32 v230, 0x7149f2ca
	v_add_u32_e32 v197, v173, v183
	v_add_u32_e32 v231, v173, v184
	v_add3_u32 v208, v177, v176, v138
	v_add3_u32 v209, v178, v176, v138
	v_add3_u32 v210, v180, v176, v138
	v_add3_u32 v211, v181, v176, v138
	v_add_u32_e32 v208, s84, v208
	v_add_u32_e32 v209, s84, v209
	v_add_u32_e32 v210, s84, v210
	v_add_u32_e32 v211, s84, v211
	v_lshlrev_b32_e32 v127, 2, v185
	v_add_u32_e32 v198, s43, v186
	v_add_u32_e32 v198, s14, v198
	v_mad_i64_i32 v[198:199], s[0:1], v198, s20, v[136:137]
	s_nop 1
	v_add_co_u32_e32 v198, vcc, 0x1000, v198
	s_nop 1
	v_addc_co_u32_e32 v199, vcc, 0, v199, vcc
	s_nop 1
	v_readfirstlane_b32 s98, v198
	v_readfirstlane_b32 s99, v199
	s_nop 1
	v_subrev_u32_e32 v198, s98, v198
	v_add_u32_e32 v199, 0x38000, v198
	s_and_b32 s0, s23, 1
	s_lshl_b32 s1, s0, 14
	v_lshl_add_u32 v129, s0, 8, v175
	v_add_u32_e32 v5, s1, v197
	v_add_u32_e32 v4, s1, v231
	ds_read_b128 v[214:217], v129 offset:32768
	ds_read_b128 v[218:221], v129 offset:32832
	ds_read_b128 v[222:225], v129 offset:32896
	ds_read_b128 v[226:229], v129 offset:32960
	ds_read_b128 v[240:243], v5
	ds_read_b128 v[244:247], v5 offset:2048
	ds_read_b128 v[248:251], v4
	ds_read_b128 v[252:255], v4 offset:2048
	s_branch .LBB0_709
.LBB0_709:
	s_and_b32 s69, s23, 1
	s_lshl_b32 s68, s69, 14
	v_add_u32_e32 v5, s68, v197
	v_add_u32_e32 v4, s68, v231
	ds_read_b128 v[114:117], v5 offset:4096
	ds_read_b128 v[118:121], v5 offset:6144
	ds_read_b128 v[122:125], v4 offset:4096
	ds_read_b128 v[188:191], v4 offset:6144
	s_waitcnt lgkmcnt(4)
	v_mfma_f32_16x16x32_bf16 v[102:105], v[240:243], v[6:9], v[214:217]
	s_waitcnt vmcnt(6)
	v_mfma_f32_16x16x32_bf16 v[86:89], v[240:243], v[14:17], v[214:217]
	v_mfma_f32_16x16x32_bf16 v[98:101], v[244:247], v[6:9], v[218:221]
	v_mfma_f32_16x16x32_bf16 v[82:85], v[244:247], v[14:17], v[218:221]
	v_mfma_f32_16x16x32_bf16 v[102:105], v[248:251], v[10:13], v[102:105]
	s_waitcnt vmcnt(5)
	v_mfma_f32_16x16x32_bf16 v[86:89], v[248:251], v[18:21], v[86:89]
	v_mfma_f32_16x16x32_bf16 v[98:101], v[252:255], v[10:13], v[98:101]
	v_mfma_f32_16x16x32_bf16 v[82:85], v[252:255], v[18:21], v[82:85]
	s_waitcnt lgkmcnt(3)
	v_mfma_f32_16x16x32_bf16 v[110:113], v[114:117], v[6:9], v[222:225]
	v_mfma_f32_16x16x32_bf16 v[94:97], v[114:117], v[14:17], v[222:225]
	s_waitcnt lgkmcnt(2)
	v_mfma_f32_16x16x32_bf16 v[106:109], v[118:121], v[6:9], v[226:229]
	v_mfma_f32_16x16x32_bf16 v[90:93], v[118:121], v[14:17], v[226:229]
	s_waitcnt lgkmcnt(1)
	v_mfma_f32_16x16x32_bf16 v[110:113], v[122:125], v[10:13], v[110:113]
	v_mfma_f32_16x16x32_bf16 v[94:97], v[122:125], v[18:21], v[94:97]
	s_waitcnt lgkmcnt(0)
	v_mfma_f32_16x16x32_bf16 v[106:109], v[188:191], v[10:13], v[106:109]
	v_mfma_f32_16x16x32_bf16 v[90:93], v[188:191], v[18:21], v[90:93]
	s_cmp_eq_u32 s23, 0
	s_cbranch_scc1 .LBB0_713
	s_xor_b32 s70, s69, 1
	s_lshl_b32 s0, s70, 14
	s_add_i32 s0, s0, 0
	v_add3_u32 v4, s0, v170, v172
	v_add_u32_e32 v5, s0, v171
	s_waitcnt vmcnt(4)
	ds_write_b128 v4, v[58:61]
	s_waitcnt vmcnt(3)
	ds_write_b128 v5, v[62:65] offset:8192
	s_waitcnt vmcnt(2)
	ds_write_b128 v4, v[70:73] offset:4096
	s_waitcnt vmcnt(1)
	ds_write_b128 v5, v[74:77] offset:12288
	s_and_saveexec_b64 s[0:1], s[10:11]
	s_cbranch_execz .LBB0_712
	v_lshl_add_u32 v4, s70, 8, v182
	s_waitcnt vmcnt(0)
	v_xor_b32_e32 v179, 0x80000000, v179
	ds_write_b32 v4, v179 offset:32768

; __device__ __forceinline__ void attn_block(const Params& P, int bh, int qb, unsigned char* smem) {
;     ...
;     auto load_tile = [&](int kv) {
;         const int key0 = kv * 64 + srow0, key1 = key0 + 32;
;         const bf16_t* p0 = z + (size_t)(b * L + (key0 < L ? key0 : L - 1)) * NZ + h * 64 + sch * 8;
;         const bf16_t* p1 = z + (size_t)(b * L + (key1 < L ? key1 : L - 1)) * NZ + h * 64 + sch * 8;
;         rk0 = *(const uint4*)(p0 + ZC_FK); rv0 = *(const uint4*)(p0 + ZC_FV);
;         rk1 = *(const uint4*)(p1 + ZC_FK); rv1 = *(const uint4*)(p1 + ZC_FV);
;         const int keyc = kv * 64 + (tid & 63);
;         rc = cum[keyc < L ? keyc : L - 1];
;     };
.LBB0_713:
	s_cmp_lt_u32 s23, 2
	s_cbranch_scc1 .LBB0_715
	global_load_dwordx4 v[58:61], v198, s[98:99] offset:1024
	global_load_dwordx4 v[62:65], v198, s[98:99] offset:2048
	global_load_dwordx4 v[70:73], v199, s[98:99] offset:1024
	global_load_dwordx4 v[74:77], v199, s[98:99] offset:2048
	v_lshl_add_u32 v4, s43, 2, v127
	s_sub_u32 s98, s98, 0x70000
	s_subb_u32 s99, s99, 0
	global_load_dword v179, v4, s[12:13]

; __device__ __forceinline__ void attn_block(const Params& P, int bh, int qb, unsigned char* smem) {
;     ...
;         bf16x8 pf[2][2];
; #pragma unroll
;         for (int u = 0; u < 2; ++u) {
;             float mx = -INFINITY;
; #pragma unroll
;             for (int c = 0; c < 4; ++c) {
;                 sa[u][c] -= ck[c];
;                 mx = fmaxf(mx, fmaxf(fmaxf(sa[u][c][0], sa[u][c][1]), fmaxf(sa[u][c][2], sa[u][c][3])));
;             }
;             mx = x4_max(mx);
;             if (__builtin_amdgcn_ballot_w64(mx > m[u]) != 0ull) {
;                 const float mn = fmaxf(m[u], mx);
;                 const float alpha = __builtin_amdgcn_exp2f(m[u] - mn);
;                 m[u] = mn;
; #pragma unroll
;                 for (int c = 0; c < 5; ++c) o[u][c] *= alpha;
;             }
.LBB0_717:
	s_nop 1
	v_max3_f32 v236, v102, v103, v104
	v_max3_f32 v237, v105, v98, v99
	v_max3_f32 v238, v100, v101, v110
	v_max3_f32 v239, v111, v112, v113
	v_max3_f32 v128, v106, v107, v108
	v_max3_f32 v236, v236, v237, v109
	v_max3_f32 v238, v238, v239, v128
	v_max_f32_e32 v236, v236, v238
	v_mov_b32_e32 v237, v236
	s_nop 1
	v_permlane32_swap_b32_e32 v236, v237
	v_max_f32_e32 v236, v236, v237
	v_mov_b32_e32 v237, v236
	s_nop 1
	v_permlane16_swap_b32_e32 v236, v237
	v_max_f32_e32 v236, v236, v237
	v_cmp_gt_f32_e32 vcc, v236, v187
	s_cbranch_vccz .LBB0_719
	v_max_f32_e32 v237, v187, v236
	v_sub_f32_e32 v236, v187, v237
	v_exp_f32_e32 v236, v236
	v_mov_b32_e32 v187, v237
	v_xor_b32_e32 v196, 0x80000000, v237
	v_pk_mul_f32 v[68:69], v[68:69], v[236:237] op_sel_hi:[1,0]
	v_pk_mul_f32 v[66:67], v[66:67], v[236:237] op_sel_hi:[1,0]
	v_pk_mul_f32 v[52:53], v[52:53], v[236:237] op_sel_hi:[1,0]
	v_pk_mul_f32 v[50:51], v[50:51], v[236:237] op_sel_hi:[1,0]
	v_pk_mul_f32 v[48:49], v[48:49], v[236:237] op_sel_hi:[1,0]
	v_pk_mul_f32 v[46:47], v[46:47], v[236:237] op_sel_hi:[1,0]
	v_pk_mul_f32 v[44:45], v[44:45], v[236:237] op_sel_hi:[1,0]
	v_pk_mul_f32 v[42:43], v[42:43], v[236:237] op_sel_hi:[1,0]
	v_pk_mul_f32 v[80:81], v[80:81], v[236:237] op_sel_hi:[1,0]
	v_pk_mul_f32 v[78:79], v[78:79], v[236:237] op_sel_hi:[1,0]
.LBB0_719:
	v_max3_f32 v236, v86, v87, v88
	v_max3_f32 v237, v89, v82, v83
	v_max3_f32 v238, v84, v85, v94
	v_max3_f32 v239, v95, v96, v97
	v_max3_f32 v128, v90, v91, v92
	v_max3_f32 v236, v236, v237, v93
	v_max3_f32 v238, v238, v239, v128
	v_max_f32_e32 v236, v236, v238
	v_mov_b32_e32 v237, v236
	s_nop 1
	v_permlane32_swap_b32_e32 v236, v237
	v_max_f32_e32 v236, v236, v237
	v_mov_b32_e32 v237, v236
	s_nop 1
	v_permlane16_swap_b32_e32 v236, v237
	v_max_f32_e32 v236, v236, v237
	v_cmp_gt_f32_e32 vcc, v236, v2
	s_cbranch_vccz .LBB0_708
	v_max_f32_e32 v237, v2, v236
	v_sub_f32_e32 v236, v2, v237
	v_exp_f32_e32 v236, v236
	v_mov_b32_e32 v2, v237
	v_xor_b32_e32 v230, 0x80000000, v237
	v_pk_mul_f32 v[36:37], v[36:37], v[236:237] op_sel_hi:[1,0]
	v_pk_mul_f32 v[34:35], v[34:35], v[236:237] op_sel_hi:[1,0]
	v_pk_mul_f32 v[32:33], v[32:33], v[236:237] op_sel_hi:[1,0]
	v_pk_mul_f32 v[30:31], v[30:31], v[236:237] op_sel_hi:[1,0]
	v_pk_mul_f32 v[28:29], v[28:29], v[236:237] op_sel_hi:[1,0]
	v_pk_mul_f32 v[26:27], v[26:27], v[236:237] op_sel_hi:[1,0]
	v_pk_mul_f32 v[24:25], v[24:25], v[236:237] op_sel_hi:[1,0]
	v_pk_mul_f32 v[22:23], v[22:23], v[236:237] op_sel_hi:[1,0]
	v_pk_mul_f32 v[40:41], v[40:41], v[236:237] op_sel_hi:[1,0]
	v_pk_mul_f32 v[38:39], v[38:39], v[236:237] op_sel_hi:[1,0]
; __device__ __forceinline__ unsigned cvt_pk_bf16(float lo, float hi) { f32x2 v = {lo, hi}; bf16x2v b = __builtin_convertvector(v, bf16x2v); return __builtin_bit_cast(unsigned, b); }
; __device__ __forceinline__ void attn_block(const Params& P, int bh, int qb, unsigned char* smem) {
;     ...
;         const int buf = kv & 1;
;         const unsigned char* sK = smem + buf * 16384; const unsigned char* sV = sK + 8192;
;         const float* sck = (const float*)(smem + 32768 + buf * 256);
;     ...
;             const float mn = m[u];
; #pragma unroll
;             for (int c = 0; c < 4; ++c)
; #pragma unroll
;                 for (int r = 0; r < 4; ++r) sa[u][c][r] = __builtin_amdgcn_exp2f(sa[u][c][r] - mn);
; #pragma unroll
;             for (int s2 = 0; s2 < 2; ++s2) {
;                 uint4 uu;
;                 uu.x = cvt_pk_bf16(sa[u][2 * s2][0], sa[u][2 * s2][1]); uu.y = cvt_pk_bf16(sa[u][2 * s2][2], sa[u][2 * s2][3]);
;                 uu.z = cvt_pk_bf16(sa[u][2 * s2 + 1][0], sa[u][2 * s2 + 1][1]); uu.w = cvt_pk_bf16(sa[u][2 * s2 + 1][2], sa[u][2 * s2 + 1][3]);
;                 pf[u][s2] = __builtin_bit_cast(bf16x8, uu);
;             }
;         }
;         {
;             uint2 vr[4][4];
;             tr_read_4c(sV, g, lr, vr);
; #pragma unroll
;             for (int c = 0; c < 4; ++c)
; #pragma unroll
;                 for (int s2 = 0; s2 < 2; ++s2) {
;                     const bf16x8 vf = tr_pair(vr[c][2 * s2], vr[c][2 * s2 + 1]);
;                     o[0][c] = __builtin_amdgcn_mfma_f32_16x16x32_bf16(vf, pf[0][s2], o[0][c], 0, 0, 0);
;                     o[1][c] = __builtin_amdgcn_mfma_f32_16x16x32_bf16(vf, pf[1][s2], o[1][c], 0, 0, 0);
;                 }
; #pragma unroll
;             for (int s2 = 0; s2 < 2; ++s2) {
;                 o[0][4] = __builtin_amdgcn_mfma_f32_16x16x32_bf16(vones, pf[0][s2], o[0][4], 0, 0, 0);
;                 o[1][4] = __builtin_amdgcn_mfma_f32_16x16x32_bf16(vones, pf[1][s2], o[1][4], 0, 0, 0);
;             }
;         }
;         __syncthreads();
.LBB0_708:
	v_add_u32_e32 v4, s68, v208
	v_add_u32_e32 v5, s68, v209
	v_add_u32_e32 v128, s68, v210
	v_add_u32_e32 v129, s68, v211
	ds_read_b64_tr_b16 v[188:189], v4
	ds_read_b64_tr_b16 v[190:191], v4 offset:2048
	ds_read_b64_tr_b16 v[192:193], v4 offset:4096
	ds_read_b64_tr_b16 v[194:195], v4 offset:6144
	ds_read_b64_tr_b16 v[114:115], v5
	ds_read_b64_tr_b16 v[116:117], v5 offset:2048
	ds_read_b64_tr_b16 v[118:119], v5 offset:4096
	ds_read_b64_tr_b16 v[120:121], v5 offset:6144
	ds_read_b64_tr_b16 v[122:123], v128
	ds_read_b64_tr_b16 v[124:125], v128 offset:2048
	ds_read_b64_tr_b16 v[200:201], v128 offset:4096
	ds_read_b64_tr_b16 v[202:203], v128 offset:6144
	ds_read_b64_tr_b16 v[204:205], v129
	ds_read_b64_tr_b16 v[206:207], v129 offset:2048
	ds_read_b64_tr_b16 v[232:233], v129 offset:4096
	ds_read_b64_tr_b16 v[234:235], v129 offset:6144
	v_pk_add_f32 v[102:103], v[102:103], v[196:197] op_sel_hi:[1,0]
	v_pk_add_f32 v[104:105], v[104:105], v[196:197] op_sel_hi:[1,0]
	v_pk_add_f32 v[98:99], v[98:99], v[196:197] op_sel_hi:[1,0]
	v_pk_add_f32 v[100:101], v[100:101], v[196:197] op_sel_hi:[1,0]
	v_pk_add_f32 v[110:111], v[110:111], v[196:197] op_sel_hi:[1,0]
	v_pk_add_f32 v[112:113], v[112:113], v[196:197] op_sel_hi:[1,0]
	v_pk_add_f32 v[106:107], v[106:107], v[196:197] op_sel_hi:[1,0]
	v_pk_add_f32 v[108:109], v[108:109], v[196:197] op_sel_hi:[1,0]
	v_exp_f32_e32 v102, v102
	v_exp_f32_e32 v103, v103
	v_exp_f32_e32 v104, v104
	v_exp_f32_e32 v105, v105
	v_exp_f32_e32 v98, v98
	v_exp_f32_e32 v99, v99
	v_exp_f32_e32 v100, v100
	v_exp_f32_e32 v101, v101
	v_exp_f32_e32 v110, v110
	v_exp_f32_e32 v111, v111
	v_exp_f32_e32 v112, v112
	v_exp_f32_e32 v113, v113
	v_exp_f32_e32 v106, v106
	v_exp_f32_e32 v107, v107
	v_exp_f32_e32 v108, v108
	v_exp_f32_e32 v109, v109
	v_cvt_pk_bf16_f32 v102, v102, v103
	v_cvt_pk_bf16_f32 v103, v104, v105
	v_cvt_pk_bf16_f32 v104, v98, v99
	v_cvt_pk_bf16_f32 v105, v100, v101
	v_cvt_pk_bf16_f32 v110, v110, v111
	v_cvt_pk_bf16_f32 v111, v112, v113
	v_cvt_pk_bf16_f32 v112, v106, v107
	v_cvt_pk_bf16_f32 v113, v108, v109
	v_pk_add_f32 v[86:87], v[86:87], v[230:231] op_sel_hi:[1,0]
	v_pk_add_f32 v[88:89], v[88:89], v[230:231] op_sel_hi:[1,0]
	v_pk_add_f32 v[82:83], v[82:83], v[230:231] op_sel_hi:[1,0]
	v_pk_add_f32 v[84:85], v[84:85], v[230:231] op_sel_hi:[1,0]
	v_pk_add_f32 v[94:95], v[94:95], v[230:231] op_sel_hi:[1,0]
	v_pk_add_f32 v[96:97], v[96:97], v[230:231] op_sel_hi:[1,0]
	v_pk_add_f32 v[90:91], v[90:91], v[230:231] op_sel_hi:[1,0]
	v_pk_add_f32 v[92:93], v[92:93], v[230:231] op_sel_hi:[1,0]
	s_waitcnt lgkmcnt(0)
	v_mfma_f32_16x16x32_bf16 v[66:69], v[188:191], v[102:105], v[66:69]
	v_exp_f32_e32 v86, v86
	v_exp_f32_e32 v87, v87
	v_exp_f32_e32 v88, v88
	v_mfma_f32_16x16x32_bf16 v[50:53], v[114:117], v[102:105], v[50:53]
	v_exp_f32_e32 v89, v89
	v_exp_f32_e32 v82, v82
	v_exp_f32_e32 v83, v83
	v_mfma_f32_16x16x32_bf16 v[46:49], v[122:125], v[102:105], v[46:49]
	s_barrier
	v_exp_f32_e32 v84, v84
	v_exp_f32_e32 v85, v85
	v_exp_f32_e32 v94, v94
	v_mfma_f32_16x16x32_bf16 v[42:45], v[204:207], v[102:105], v[42:45]
	v_exp_f32_e32 v95, v95
	v_exp_f32_e32 v96, v96
	v_exp_f32_e32 v97, v97
	v_mfma_f32_16x16x32_bf16 v[78:81], v[54:57], v[102:105], v[78:81]
	v_exp_f32_e32 v90, v90
	v_exp_f32_e32 v91, v91
	v_mfma_f32_16x16x32_bf16 v[66:69], v[192:195], v[110:113], v[66:69]
	v_exp_f32_e32 v92, v92
	v_exp_f32_e32 v93, v93
	v_mfma_f32_16x16x32_bf16 v[50:53], v[118:121], v[110:113], v[50:53]
	v_cvt_pk_bf16_f32 v86, v86, v87
	v_cvt_pk_bf16_f32 v87, v88, v89
	v_mfma_f32_16x16x32_bf16 v[46:49], v[200:203], v[110:113], v[46:49]
	v_cvt_pk_bf16_f32 v88, v82, v83
	v_cvt_pk_bf16_f32 v89, v84, v85
	v_mfma_f32_16x16x32_bf16 v[42:45], v[232:235], v[110:113], v[42:45]
	v_cvt_pk_bf16_f32 v94, v94, v95
	v_cvt_pk_bf16_f32 v95, v96, v97
	v_mfma_f32_16x16x32_bf16 v[78:81], v[54:57], v[110:113], v[78:81]
	v_cvt_pk_bf16_f32 v96, v90, v91
	v_cvt_pk_bf16_f32 v97, v92, v93
	s_add_i32 s23, s23, -1
	s_sub_i32 s43, s43, 64
	s_and_b32 s0, s23, 1
	s_lshl_b32 s1, s0, 14
	v_lshl_add_u32 v129, s0, 8, v175
	v_add_u32_e32 v5, s1, v197
	v_add_u32_e32 v4, s1, v231
	s_cmp_eq_u32 s23, -1
	v_mfma_f32_16x16x32_bf16 v[34:37], v[188:191], v[86:89], v[34:37]
	ds_read_b128 v[214:217], v129 offset:32768
	v_mfma_f32_16x16x32_bf16 v[30:33], v[114:117], v[86:89], v[30:33]
	ds_read_b128 v[218:221], v129 offset:32832
	v_mfma_f32_16x16x32_bf16 v[26:29], v[122:125], v[86:89], v[26:29]
	ds_read_b128 v[222:225], v129 offset:32896
	v_mfma_f32_16x16x32_bf16 v[22:25], v[204:207], v[86:89], v[22:25]
	ds_read_b128 v[226:229], v129 offset:32960
	v_mfma_f32_16x16x32_bf16 v[38:41], v[54:57], v[86:89], v[38:41]
	ds_read_b128 v[240:243], v5
	v_mfma_f32_16x16x32_bf16 v[34:37], v[192:195], v[94:97], v[34:37]
	ds_read_b128 v[244:247], v5 offset:2048
	v_mfma_f32_16x16x32_bf16 v[30:33], v[118:121], v[94:97], v[30:33]
	ds_read_b128 v[248:251], v4
	v_mfma_f32_16x16x32_bf16 v[26:29], v[200:203], v[94:97], v[26:29]
	ds_read_b128 v[252:255], v4 offset:2048
	v_mfma_f32_16x16x32_bf16 v[22:25], v[232:235], v[94:97], v[22:25]
	v_mfma_f32_16x16x32_bf16 v[38:41], v[54:57], v[94:97], v[38:41]
	s_cbranch_scc0 .LBB0_709
